# dilated stage top: next stage's K/V loads issued before the LDS-publishing barrier instead of after it
# baseline (speedup 1.0000x reference)
; #define LAS __attribute__((address_space(3)))
; template <int D, int STR>
; DI void put_rows128(LAS unsigned char* dst, const RowRegs<D>& R, int tid) {
;     constexpr int CPR = D / 8, NCH = 128 * CPR / NTHR;
; #pragma unroll
;     for (int k = 0; k < NCH; ++k) { const int c = tid + k * NTHR, r = c / CPR, q = c % CPR; *(LAS u32x4*)(dst + r * STR + q * 16) = R.v[k]; }
; }
; DI void dil_unit(Frame& F, const DilItem& it, bool has_next, const DilItem& nx, RowRegs<128>& RK, RowRegs<128>& RV) {
;     ...
;     for (int st = st_lo; st < 3; ++st) {
;         const int cbase = -128 + 128 * st;
;         __syncthreads();
;         put_rows128<128, KSTR128>(Ks, RK, F.tid); put_rows128<128, VSTR128>(Vs, RV, F.tid);
;         __syncthreads();
.LBB0_1093:
	v_add_u32_e32 v64, v181, v182
	v_add_u32_e32 v65, v183, v182
	s_waitcnt lgkmcnt(0)
	s_barrier
	s_waitcnt vmcnt(7)
	ds_write_b128 v64, v[80:83]
	s_waitcnt vmcnt(6)
	ds_write_b128 v65, v[84:87]
	s_waitcnt vmcnt(5)
	ds_write_b128 v64, v[88:91] offset:17408
	v_add_u32_e32 v64, v184, v182
	s_cmp_eq_u32 s66, 2
	s_waitcnt vmcnt(4)
	ds_write_b128 v64, v[92:95]
	s_waitcnt vmcnt(3)
	ds_write_b128 v188, v[96:99] offset:36864
	s_waitcnt vmcnt(2)
	ds_write_b128 v189, v[100:103] offset:36864
	s_waitcnt vmcnt(1)
	ds_write_b128 v190, v[104:107] offset:36864
	s_waitcnt vmcnt(0)
	ds_write_b128 v191, v[108:111] offset:36864
	s_cbranch_scc1 .LBB0_1095
	s_lshl_b32 s6, s66, 7
	s_add_i32 s6, s6, s12
	s_lshl_b32 s6, s6, s43
	s_or_b32 s46, s6, s41
	s_mov_b64 s[6:7], 0
	s_mov_b64 s[48:49], -1
	s_branch .LBB0_1096

; template <int D, int STR>
; DI void load_q_frags(Frame& F, bf16x8* qf, const bf16* g0, size_t gstride, LAS unsigned char* buf) {
;     ...
;     for (int hb = 0; hb < NCH; hb += 4) { u32x4 v[4];
; #pragma unroll
;       for (int k = 0; k < 4; ++k) { const int c = tid_ + (hb + k) * NTHR, r = c / CPR, q = c % CPR; v[k] = *(const u32x4*)(g0 + (size_t)r * gstride + q * 8); }
; DI void dil_unit(Frame& F, const DilItem& it, bool has_next, const DilItem& nx, RowRegs<128>& RK, RowRegs<128>& RV) {
;     ...
;         __syncthreads();
;         if (st < 2) { size_t gs; const bf16* kg = dil_kptr(F, it, st + 1, gs);
;             fetch_rows128<128>(RK, kg, gs, F.tid); fetch_rows128<128>(RV, kg + (size_t)MTOK * 2048, gs, F.tid); }
;         else if (has_next) { size_t gs; const bf16* kg = dil_kptr(F, nx, nx.nb == 0 ? 1 : 0, gs);
;             fetch_rows128<128>(RK, kg, gs, F.tid); fetch_rows128<128>(RV, kg + (size_t)MTOK * 2048, gs, F.tid); }
.LBB0_1100:
	s_waitcnt lgkmcnt(0)
	s_barrier
	s_cmp_lg_u32 s66, 2
	s_cbranch_scc1 .Lqp10_skip
	s_cmp_eq_u64 s[34:35], 0
	s_cbranch_scc1 .Lqp10_skip
	v_readlane_b32 s100, v229, 56
	s_mov_b32 s101, 0
	v_readlane_b32 s98, v229, 57
	s_nop 0
	v_lshl_add_u64 v[64:65], v[150:151], 0, s[100:101]
	global_load_dword v228, v[64:65], off
	s_lshl_b32 s100, 0x100, s40
	s_sub_i32 s98, s98, s64
	s_lshl_b32 s98, s98, 8
	s_add_u32 s98, s46, s98
	s_addc_u32 s99, s47, 0
	s_sub_u32 s98, s98, 0x4000000
	s_subb_u32 s99, s99, 0
	v_lshlrev_b64 v[64:65], s40, v[152:153]
	v_lshl_add_u64 v[64:65], v[64:65], 1, s[98:99]
	v_lshl_add_u64 v[64:65], v[64:65], 0, v[148:149]
	v_lshl_add_u64 v[66:67], v[64:65], 0, s[100:101]
	global_load_dwordx4 v[208:211], v[64:65], off
	global_load_dwordx4 v[224:227], v[66:67], off
	v_lshlrev_b64 v[64:65], s40, v[154:155]
	v_lshl_add_u64 v[64:65], v[64:65], 1, s[98:99]
	v_lshl_add_u64 v[64:65], v[64:65], 0, v[148:149]
	v_lshl_add_u64 v[66:67], v[64:65], 0, s[100:101]
	global_load_dwordx4 v[212:215], v[64:65], off
	global_load_dwordx4 v[232:235], v[66:67], off
	v_lshlrev_b64 v[64:65], s40, v[156:157]
	v_lshl_add_u64 v[64:65], v[64:65], 1, s[98:99]
	v_lshl_add_u64 v[64:65], v[64:65], 0, v[148:149]
	v_lshl_add_u64 v[66:67], v[64:65], 0, s[100:101]
	global_load_dwordx4 v[216:219], v[64:65], off
	global_load_dwordx4 v[236:239], v[66:67], off
	v_lshlrev_b64 v[64:65], s40, v[158:159]
	v_lshl_add_u64 v[64:65], v[64:65], 1, s[98:99]
	v_lshl_add_u64 v[64:65], v[64:65], 0, v[148:149]
	v_lshl_add_u64 v[66:67], v[64:65], 0, s[100:101]
	global_load_dwordx4 v[220:223], v[64:65], off
	global_load_dwordx4 v[240:243], v[66:67], off
	s_mov_b32 s98, 1
	v_writelane_b32 v229, s98, 58

; #define LAS __attribute__((address_space(3)))
; template <int D, int STR>
; DI void put_rows128(LAS unsigned char* dst, const RowRegs<D>& R, int tid) {
;     constexpr int CPR = D / 8, NCH = 128 * CPR / NTHR;
; #pragma unroll
;     for (int k = 0; k < NCH; ++k) { const int c = tid + k * NTHR, r = c / CPR, q = c % CPR; *(LAS u32x4*)(dst + r * STR + q * 16) = R.v[k]; }
; }
; DI void dil_unit(Frame& F, const DilItem& it, bool has_next, const DilItem& nx, RowRegs<128>& RK, RowRegs<128>& RV) {
;     ...
;     for (int st = st_lo; st < 3; ++st) {
;         const int cbase = -128 + 128 * st;
;         __syncthreads();
;         put_rows128<128, KSTR128>(Ks, RK, F.tid); put_rows128<128, VSTR128>(Vs, RV, F.tid);
;         __syncthreads();
.LBB0_1180:
	v_add_u32_e32 v64, v180, v181
	v_add_u32_e32 v65, v182, v181
	s_waitcnt lgkmcnt(0)
	s_barrier
	s_waitcnt vmcnt(7)
	ds_write_b128 v64, v[80:83]
	s_waitcnt vmcnt(6)
	ds_write_b128 v65, v[84:87]
	s_waitcnt vmcnt(5)
	ds_write_b128 v64, v[88:91] offset:17408
	v_add_u32_e32 v64, v183, v181
	s_cmp_eq_u32 s57, 2
	s_waitcnt vmcnt(4)
	ds_write_b128 v64, v[92:95]
	s_waitcnt vmcnt(3)
	ds_write_b128 v187, v[96:99] offset:36864
	s_waitcnt vmcnt(2)
	ds_write_b128 v188, v[100:103] offset:36864
	s_waitcnt vmcnt(1)
	ds_write_b128 v189, v[104:107] offset:36864
	s_waitcnt vmcnt(0)
	ds_write_b128 v190, v[108:111] offset:36864
	s_cbranch_scc1 .LBB0_1182
	s_lshl_b32 s4, s57, 7
	s_add_i32 s38, s4, s19
	s_mov_b64 s[40:41], -1
	s_mov_b64 s[4:5], 7
	s_mov_b64 s[42:43], s[34:35]
	s_cbranch_execz .LBB0_1183
	s_branch .LBB0_1184

; template <int D, int STR>
; DI void load_q_frags(Frame& F, bf16x8* qf, const bf16* g0, size_t gstride, LAS unsigned char* buf) {
;     ...
;     for (int hb = 0; hb < NCH; hb += 4) { u32x4 v[4];
; #pragma unroll
;       for (int k = 0; k < 4; ++k) { const int c = tid_ + (hb + k) * NTHR, r = c / CPR, q = c % CPR; v[k] = *(const u32x4*)(g0 + (size_t)r * gstride + q * 8); }
; DI void dil_unit(Frame& F, const DilItem& it, bool has_next, const DilItem& nx, RowRegs<128>& RK, RowRegs<128>& RV) {
;     ...
;         __syncthreads();
;         if (st < 2) { size_t gs; const bf16* kg = dil_kptr(F, it, st + 1, gs);
;             fetch_rows128<128>(RK, kg, gs, F.tid); fetch_rows128<128>(RV, kg + (size_t)MTOK * 2048, gs, F.tid); }
;         else if (has_next) { size_t gs; const bf16* kg = dil_kptr(F, nx, nx.nb == 0 ? 1 : 0, gs);
;             fetch_rows128<128>(RK, kg, gs, F.tid); fetch_rows128<128>(RV, kg + (size_t)MTOK * 2048, gs, F.tid); }
.LBB0_1186:
	s_waitcnt lgkmcnt(0)
	s_barrier
	s_cmp_lg_u32 s57, 2
	s_cbranch_scc1 .Lqp11_skip
	s_cmp_eq_u64 s[30:31], 0
	s_cbranch_scc1 .Lqp11_skip
	v_readlane_b32 s100, v229, 56
	s_mov_b32 s101, 0
	v_readlane_b32 s98, v229, 57
	s_nop 0
	v_lshl_add_u64 v[64:65], v[150:151], 0, s[100:101]
	global_load_dword v228, v[64:65], off
	s_lshl_b32 s100, 0x100, s8
	s_sub_i32 s98, s98, s29
	s_lshl_b32 s98, s98, 8
	s_add_u32 s98, s38, s98
	s_addc_u32 s99, s39, 0
	s_sub_u32 s98, s98, 0x4000000
	s_subb_u32 s99, s99, 0
	v_lshlrev_b64 v[64:65], s8, v[152:153]
	v_lshl_add_u64 v[64:65], v[64:65], 1, s[98:99]
	v_lshl_add_u64 v[64:65], v[64:65], 0, v[148:149]
	v_lshl_add_u64 v[66:67], v[64:65], 0, s[100:101]
	global_load_dwordx4 v[208:211], v[64:65], off
	global_load_dwordx4 v[224:227], v[66:67], off
	v_lshlrev_b64 v[64:65], s8, v[154:155]
	v_lshl_add_u64 v[64:65], v[64:65], 1, s[98:99]
	v_lshl_add_u64 v[64:65], v[64:65], 0, v[148:149]
	v_lshl_add_u64 v[66:67], v[64:65], 0, s[100:101]
	global_load_dwordx4 v[212:215], v[64:65], off
	global_load_dwordx4 v[232:235], v[66:67], off
	v_lshlrev_b64 v[64:65], s8, v[156:157]
	v_lshl_add_u64 v[64:65], v[64:65], 1, s[98:99]
	v_lshl_add_u64 v[64:65], v[64:65], 0, v[148:149]
	v_lshl_add_u64 v[66:67], v[64:65], 0, s[100:101]
	global_load_dwordx4 v[216:219], v[64:65], off
	global_load_dwordx4 v[236:239], v[66:67], off
	v_lshlrev_b64 v[64:65], s8, v[158:159]
	v_lshl_add_u64 v[64:65], v[64:65], 1, s[98:99]
	v_lshl_add_u64 v[64:65], v[64:65], 0, v[148:149]
	v_lshl_add_u64 v[66:67], v[64:65], 0, s[100:101]
	global_load_dwordx4 v[220:223], v[64:65], off
	global_load_dwordx4 v[240:243], v[66:67], off
	s_mov_b32 s98, 1
	v_writelane_b32 v229, s98, 58
